# gate/up unit-loop header: next-unit decode temporaries renamed from v[2:3] (data registers of the epilogue's last store) to dead fragment registers, so decode VALU writes do not wait on pending store
# speedup vs baseline: 1.0027x; 1.0027x over previous
.LBB0_1057:
	s_add_i32 s65, s65, 1
	s_mul_i32 s4, s65, s39
	s_mul_hi_u32 s5, s65, s36
	s_add_i32 s5, s5, s4
	s_mul_i32 s4, s65, s36
	s_add_u32 s20, s4, s37
	s_addc_u32 s21, s5, s66
	v_mov_b64_e32 v[142:143], 0x580
	v_cmp_lt_i64_e64 s[4:5], s[20:21], v[142:143]
	v_mov_b64_e32 v[142:143], 0x57f
	v_cmp_gt_i64_e32 vcc, s[20:21], v[142:143]
	s_cbranch_vccnz .LBB0_1059
	s_ashr_i32 s16, s20, 31
	s_lshr_b32 s16, s16, 29
	s_add_i32 s16, s20, s16
	s_ashr_i32 s17, s16, 3
	s_and_b32 s16, s16, -8
	s_sub_i32 s16, s20, s16
	s_cmp_lt_i32 s16, 0
	s_cselect_b32 s18, s3, 0xb0
	s_mul_i32 s16, s16, s18
	s_add_i32 s16, s16, s17
	s_mul_hi_i32 s17, s16, 0x2e8ba2e9
	s_lshr_b32 s18, s17, 31
	s_ashr_i32 s17, s17, 6
	s_add_i32 s17, s17, s18
	s_lshl_b32 s18, s17, 3
	s_sub_i32 s19, 32, s18
	s_min_i32 s19, s19, 8
	s_abs_i32 s20, s19
	v_cvt_f32_u32_e32 v142, s20
	s_sub_i32 s22, 0, s20
	s_mulk_i32 s17, 0x160
	s_sub_i32 s17, s16, s17
	v_rcp_iflag_f32_e32 v142, v142
	s_abs_i32 s16, s17
	s_xor_b32 s21, s17, s19
	s_ashr_i32 s21, s21, 31
	v_mul_f32_e32 v142, 0x4f7ffffe, v142
	v_cvt_u32_f32_e32 v142, v142
	s_nop 0
	v_readfirstlane_b32 s23, v142
	s_mul_i32 s22, s22, s23
	s_mul_hi_u32 s22, s23, s22
	s_add_i32 s23, s23, s22
	s_mul_hi_u32 s22, s16, s23
	s_mul_i32 s23, s22, s20
	s_sub_i32 s16, s16, s23
	s_add_i32 s30, s22, 1
	s_sub_i32 s23, s16, s20
	s_cmp_ge_u32 s16, s20
	s_cselect_b32 s22, s30, s22
	s_cselect_b32 s16, s23, s16
	s_add_i32 s23, s22, 1
	s_cmp_ge_u32 s16, s20
	s_cselect_b32 s16, s23, s22
	s_xor_b32 s16, s16, s21
	s_sub_i32 s16, s16, s21
	s_mul_i32 s19, s16, s19
	s_sub_i32 s17, s17, s19
	s_add_i32 s18, s18, s17
